# scaled GEMM epilogues (phases 6, 9): output tile leaves through a wave-private swizzled LDS image as 128-byte row pieces (dwordx4) instead of 32-byte pieces; ssq loads hoisted
# speedup vs baseline: 1.2068x; 1.0169x over previous
; DEVI unsigned pack2(float a, float b) { return (unsigned)f2bf(a) | ((unsigned)f2bf(b) << 16); }
; DEVI void phase_scaled(const Params& p, unsigned char* smem, const u16* A, const u16* Wt, int ntn, const float* ssq, u16* outp, int ldo) {
;     ...
; #pragma unroll
;     for (int mi = 0; mi < 4; ++mi) {
;       const int m = m0 + wm * 64 + 16 * mi + col;
;       const float rstd = rsqrtf(ssq[m] * (1.f / D) + 1e-6f);
; #pragma unroll
;       for (int ni = 0; ni < 4; ++ni) {
;         const int n = n0 + wn * 64 + 16 * ni + 4 * quad;
;         const f32x4 v = acc[ni][mi];
;         uint2 pk; pk.x = pack2(v[0] * rstd, v[1] * rstd); pk.y = pack2(v[2] * rstd, v[3] * rstd);
;         *(uint2*)(outp + (size_t)m * ldo + n) = pk;
;       }
;     }
.LBB0_961:
	v_and_b32_e32 v200, 63, v210
	v_lshrrev_b32_e32 v201, 6, v210
	v_and_b32_e32 v202, 15, v200
	v_lshrrev_b32_e32 v203, 4, v200
	v_lshlrev_b32_e32 v204, 13, v201
	v_lshl_add_u32 v204, v202, 7, v204
	v_and_b32_e32 v205, 1, v203
	v_lshl_add_u32 v204, v205, 3, v204
	v_lshrrev_b32_e32 v205, 1, v203
	v_and_b32_e32 v206, 7, v202
	v_xor_b32_e32 v205, v205, v206
	v_xor_b32_e32 v207, 0, v205
	v_lshl_add_u32 v180, v207, 4, v204
	v_xor_b32_e32 v207, 2, v205
	v_lshl_add_u32 v181, v207, 4, v204
	v_xor_b32_e32 v207, 4, v205
	v_lshl_add_u32 v182, v207, 4, v204
	v_xor_b32_e32 v207, 6, v205
	v_lshl_add_u32 v183, v207, 4, v204
	v_lshrrev_b32_e32 v206, 3, v200
	v_and_b32_e32 v207, 7, v200
	v_lshlrev_b32_e32 v184, 13, v201
	v_lshl_add_u32 v184, v206, 7, v184
	v_lshl_add_u32 v184, v207, 4, v184
	v_xor_b32_e32 v207, v207, v206
	v_lshlrev_b32_e32 v207, 4, v207
	v_mul_lo_u32 v185, v206, s15
	v_add_u32_e32 v185, v185, v207
	v_mov_b32_e32 v186, s15
	v_lshlrev_b32_e32 v186, 3, v186
	v_ashrrev_i32_e32 v64, 1, v104
	v_and_b32_e32 v64, 0xffffffc0, v64
	v_add_u32_e32 v64, s19, v64
	v_and_or_b32 v70, v104, 15, v64
	v_ashrrev_i32_e32 v71, 31, v70
	v_lshl_add_u64 v[74:75], v[70:71], 2, s[48:49]
	global_load_dword v64, v[74:75], off
	global_load_dword v174, v[74:75], off offset:64
	global_load_dword v175, v[74:75], off offset:128
	global_load_dword v176, v[74:75], off offset:192
	v_lshrrev_b32_e32 v78, 2, v104
	v_and_b32_e32 v71, 64, v104
	v_mov_b32_e32 v76, v60
	v_mov_b32_e32 v60, v56
	v_mov_b32_e32 v56, v52
	v_mov_b32_e32 v52, v48
	v_and_b32_e32 v48, 12, v78
	v_or3_b32 v48, v71, v48, s18
	v_mov_b32_e32 v77, v62
	v_mov_b32_e32 v62, v61
	v_readlane_b32 s20, v248, 12
	v_mov_b32_e32 v61, v58
	v_mov_b32_e32 v58, v57
	v_mov_b32_e32 v57, v54
	v_mov_b32_e32 v54, v53
	v_mov_b32_e32 v53, v50
	v_mov_b32_e32 v50, v49
	v_readlane_b32 s21, v248, 13
	v_ashrrev_i32_e32 v49, 31, v48
	v_lshlrev_b64 v[48:49], 1, v[48:49]
	v_mov_b64_e32 v[72:73], s[20:21]
	v_mad_i64_i32 v[78:79], s[8:9], v70, s15, v[72:73]
	v_lshl_add_u64 v[78:79], v[78:79], 0, v[48:49]
	s_add_i32 s11, s11, s14
	s_cmp_lt_i32 s11, s12
	v_readlane_b32 s22, v248, 14
	v_readlane_b32 s23, v248, 15
	s_waitcnt vmcnt(0)
	v_fmamk_f32 v64, v64, 0x3a800000, v102
	v_mul_f32_e32 v71, 0x4b800000, v64
	v_cmp_gt_f32_e32 vcc, s16, v64
	s_nop 1
	v_cndmask_b32_e32 v64, v64, v71, vcc
	v_rsq_f32_e32 v64, v64
	s_nop 0
	v_mul_f32_e32 v71, 0x45800000, v64
	v_cndmask_b32_e32 v64, v64, v71, vcc
	v_pk_mul_f32 v[62:63], v[62:63], v[64:65] op_sel_hi:[1,0]
	v_pk_mul_f32 v[76:77], v[76:77], v[64:65] op_sel_hi:[1,0]
	v_pk_mul_f32 v[58:59], v[58:59], v[64:65] op_sel_hi:[1,0]
	v_pk_mul_f32 v[54:55], v[54:55], v[64:65] op_sel_hi:[1,0]
	v_pk_mul_f32 v[52:53], v[52:53], v[64:65] op_sel_hi:[1,0]
	v_pk_mul_f32 v[50:51], v[50:51], v[64:65] op_sel_hi:[1,0]
	v_and_b32_sdwa v80, v63, v103 dst_sel:DWORD dst_unused:UNUSED_PAD src0_sel:WORD_1 src1_sel:DWORD
	v_and_b32_sdwa v81, v62, v103 dst_sel:DWORD dst_unused:UNUSED_PAD src0_sel:WORD_1 src1_sel:DWORD
	v_pk_mul_f32 v[60:61], v[60:61], v[64:65] op_sel_hi:[1,0]
	v_pk_mul_f32 v[56:57], v[56:57], v[64:65] op_sel_hi:[1,0]
	v_and_b32_sdwa v64, v77, v103 dst_sel:DWORD dst_unused:UNUSED_PAD src0_sel:WORD_1 src1_sel:DWORD
	v_and_b32_sdwa v71, v76, v103 dst_sel:DWORD dst_unused:UNUSED_PAD src0_sel:WORD_1 src1_sel:DWORD
	v_and_b32_sdwa v84, v59, v103 dst_sel:DWORD dst_unused:UNUSED_PAD src0_sel:WORD_1 src1_sel:DWORD
	v_and_b32_sdwa v85, v58, v103 dst_sel:DWORD dst_unused:UNUSED_PAD src0_sel:WORD_1 src1_sel:DWORD
	v_and_b32_sdwa v88, v55, v103 dst_sel:DWORD dst_unused:UNUSED_PAD src0_sel:WORD_1 src1_sel:DWORD
	v_and_b32_sdwa v89, v54, v103 dst_sel:DWORD dst_unused:UNUSED_PAD src0_sel:WORD_1 src1_sel:DWORD
	v_and_b32_sdwa v90, v53, v103 dst_sel:DWORD dst_unused:UNUSED_PAD src0_sel:WORD_1 src1_sel:DWORD
	v_and_b32_sdwa v91, v52, v103 dst_sel:DWORD dst_unused:UNUSED_PAD src0_sel:WORD_1 src1_sel:DWORD
	v_and_b32_sdwa v92, v51, v103 dst_sel:DWORD dst_unused:UNUSED_PAD src0_sel:WORD_1 src1_sel:DWORD
	v_and_b32_sdwa v93, v50, v103 dst_sel:DWORD dst_unused:UNUSED_PAD src0_sel:WORD_1 src1_sel:DWORD
	v_add3_u32 v63, v63, v80, s17
	v_add3_u32 v62, v62, v81, s17
	v_and_b32_sdwa v82, v61, v103 dst_sel:DWORD dst_unused:UNUSED_PAD src0_sel:WORD_1 src1_sel:DWORD
	v_and_b32_sdwa v83, v60, v103 dst_sel:DWORD dst_unused:UNUSED_PAD src0_sel:WORD_1 src1_sel:DWORD
	v_and_b32_sdwa v86, v57, v103 dst_sel:DWORD dst_unused:UNUSED_PAD src0_sel:WORD_1 src1_sel:DWORD
	v_and_b32_sdwa v87, v56, v103 dst_sel:DWORD dst_unused:UNUSED_PAD src0_sel:WORD_1 src1_sel:DWORD
	v_add3_u32 v71, v76, v71, s17
	v_add3_u32 v64, v77, v64, s17
	v_add3_u32 v59, v59, v84, s17
	v_add3_u32 v58, v58, v85, s17
	v_add3_u32 v55, v55, v88, s17
	v_add3_u32 v54, v54, v89, s17
	v_add3_u32 v76, v52, v91, s17
	v_add3_u32 v77, v53, v90, s17
	v_add3_u32 v51, v51, v92, s17
	v_add3_u32 v50, v50, v93, s17
	v_and_b32_e32 v52, 0xffff0000, v63
	v_and_b32_e32 v53, 0xffff0000, v62
	v_add3_u32 v60, v60, v83, s17
	v_add3_u32 v61, v61, v82, s17
	v_add3_u32 v56, v56, v87, s17
	v_add3_u32 v57, v57, v86, s17
	v_and_b32_e32 v59, 0xffff0000, v59
	v_and_b32_e32 v58, 0xffff0000, v58
	v_and_b32_e32 v55, 0xffff0000, v55
	v_and_b32_e32 v54, 0xffff0000, v54
	v_and_b32_e32 v62, 0xffff0000, v51
	v_and_b32_e32 v63, 0xffff0000, v50
	v_or_b32_sdwa v51, v52, v64 dst_sel:DWORD dst_unused:UNUSED_PAD src0_sel:DWORD src1_sel:WORD_1
	v_or_b32_sdwa v50, v53, v71 dst_sel:DWORD dst_unused:UNUSED_PAD src0_sel:DWORD src1_sel:WORD_1
	v_or_b32_sdwa v53, v59, v61 dst_sel:DWORD dst_unused:UNUSED_PAD src0_sel:DWORD src1_sel:WORD_1
	v_or_b32_sdwa v52, v58, v60 dst_sel:DWORD dst_unused:UNUSED_PAD src0_sel:DWORD src1_sel:WORD_1
; DEVI unsigned pack2(float a, float b) { return (unsigned)f2bf(a) | ((unsigned)f2bf(b) << 16); }
; DEVI void phase_scaled(const Params& p, unsigned char* smem, const u16* A, const u16* Wt, int ntn, const float* ssq, u16* outp, int ldo) {
;     ...
; #pragma unroll
;     for (int mi = 0; mi < 4; ++mi) {
;       const int m = m0 + wm * 64 + 16 * mi + col;
;       const float rstd = rsqrtf(ssq[m] * (1.f / D) + 1e-6f);
; #pragma unroll
;       for (int ni = 0; ni < 4; ++ni) {
;         const int n = n0 + wn * 64 + 16 * ni + 4 * quad;
;         const f32x4 v = acc[ni][mi];
;         uint2 pk; pk.x = pack2(v[0] * rstd, v[1] * rstd); pk.y = pack2(v[2] * rstd, v[3] * rstd);
;         *(uint2*)(outp + (size_t)m * ldo + n) = pk;
;       }
;     }
	v_or_b32_sdwa v55, v55, v57 dst_sel:DWORD dst_unused:UNUSED_PAD src0_sel:DWORD src1_sel:WORD_1
	v_or_b32_sdwa v54, v54, v56 dst_sel:DWORD dst_unused:UNUSED_PAD src0_sel:DWORD src1_sel:WORD_1
	v_or_b32_sdwa v57, v62, v77 dst_sel:DWORD dst_unused:UNUSED_PAD src0_sel:DWORD src1_sel:WORD_1
	v_or_b32_sdwa v56, v63, v76 dst_sel:DWORD dst_unused:UNUSED_PAD src0_sel:DWORD src1_sel:WORD_1
	v_readfirstlane_b32 s98, v78
	v_readfirstlane_b32 s99, v79
	ds_write_b64 v180, v[50:51]
	ds_write_b64 v181, v[52:53]
	ds_write_b64 v182, v[54:55]
	ds_write_b64 v183, v[56:57]
	v_mov_b32_e32 v52, v174
	v_mov_b32_e32 v51, v46
	v_mov_b32_e32 v46, v45
	v_mov_b32_e32 v45, v42
	v_mov_b32_e32 v42, v41
	v_mov_b32_e32 v41, v38
	v_mov_b32_e32 v38, v37
	v_mov_b32_e32 v37, v34
	v_mov_b32_e32 v34, v33
	v_mov_b32_e32 v50, v44
	v_mov_b32_e32 v44, v40
	v_mov_b32_e32 v40, v36
	v_mov_b32_e32 v36, v32
	v_or_b32_e32 v32, 16, v70
	s_nop 0
	v_fmamk_f32 v33, v52, 0x3a800000, v102
	v_mul_f32_e32 v52, 0x4b800000, v33
	v_cmp_gt_f32_e32 vcc, s16, v33
	s_nop 1
	v_cndmask_b32_e32 v33, v33, v52, vcc
	v_rsq_f32_e32 v52, v33
	v_mad_i64_i32 v[32:33], s[8:9], v32, s15, v[72:73]
	v_lshl_add_u64 v[32:33], v[32:33], 0, v[48:49]
	v_mul_f32_e32 v53, 0x45800000, v52
	v_cndmask_b32_e32 v52, v52, v53, vcc
	v_pk_mul_f32 v[46:47], v[46:47], v[52:53] op_sel_hi:[1,0]
	v_pk_mul_f32 v[50:51], v[50:51], v[52:53] op_sel_hi:[1,0]
	v_pk_mul_f32 v[42:43], v[42:43], v[52:53] op_sel_hi:[1,0]
	v_pk_mul_f32 v[38:39], v[38:39], v[52:53] op_sel_hi:[1,0]
	v_pk_mul_f32 v[36:37], v[36:37], v[52:53] op_sel_hi:[1,0]
	v_pk_mul_f32 v[34:35], v[34:35], v[52:53] op_sel_hi:[1,0]
	v_and_b32_sdwa v54, v47, v103 dst_sel:DWORD dst_unused:UNUSED_PAD src0_sel:WORD_1 src1_sel:DWORD
	v_and_b32_sdwa v55, v46, v103 dst_sel:DWORD dst_unused:UNUSED_PAD src0_sel:WORD_1 src1_sel:DWORD
	v_pk_mul_f32 v[44:45], v[44:45], v[52:53] op_sel_hi:[1,0]
	v_pk_mul_f32 v[40:41], v[40:41], v[52:53] op_sel_hi:[1,0]
	v_and_b32_sdwa v52, v51, v103 dst_sel:DWORD dst_unused:UNUSED_PAD src0_sel:WORD_1 src1_sel:DWORD
	v_and_b32_sdwa v53, v50, v103 dst_sel:DWORD dst_unused:UNUSED_PAD src0_sel:WORD_1 src1_sel:DWORD
	v_and_b32_sdwa v58, v43, v103 dst_sel:DWORD dst_unused:UNUSED_PAD src0_sel:WORD_1 src1_sel:DWORD
	v_and_b32_sdwa v59, v42, v103 dst_sel:DWORD dst_unused:UNUSED_PAD src0_sel:WORD_1 src1_sel:DWORD
	v_and_b32_sdwa v62, v39, v103 dst_sel:DWORD dst_unused:UNUSED_PAD src0_sel:WORD_1 src1_sel:DWORD
	v_and_b32_sdwa v63, v38, v103 dst_sel:DWORD dst_unused:UNUSED_PAD src0_sel:WORD_1 src1_sel:DWORD
	v_and_b32_sdwa v64, v37, v103 dst_sel:DWORD dst_unused:UNUSED_PAD src0_sel:WORD_1 src1_sel:DWORD
	v_and_b32_sdwa v71, v36, v103 dst_sel:DWORD dst_unused:UNUSED_PAD src0_sel:WORD_1 src1_sel:DWORD
	v_and_b32_sdwa v76, v35, v103 dst_sel:DWORD dst_unused:UNUSED_PAD src0_sel:WORD_1 src1_sel:DWORD
	v_and_b32_sdwa v77, v34, v103 dst_sel:DWORD dst_unused:UNUSED_PAD src0_sel:WORD_1 src1_sel:DWORD
	v_add3_u32 v47, v47, v54, s17
	v_add3_u32 v46, v46, v55, s17
	v_and_b32_sdwa v56, v45, v103 dst_sel:DWORD dst_unused:UNUSED_PAD src0_sel:WORD_1 src1_sel:DWORD
	v_and_b32_sdwa v57, v44, v103 dst_sel:DWORD dst_unused:UNUSED_PAD src0_sel:WORD_1 src1_sel:DWORD
	v_and_b32_sdwa v60, v41, v103 dst_sel:DWORD dst_unused:UNUSED_PAD src0_sel:WORD_1 src1_sel:DWORD
	v_and_b32_sdwa v61, v40, v103 dst_sel:DWORD dst_unused:UNUSED_PAD src0_sel:WORD_1 src1_sel:DWORD
	v_add3_u32 v50, v50, v53, s17
	v_add3_u32 v51, v51, v52, s17
	v_add3_u32 v43, v43, v58, s17
	v_add3_u32 v42, v42, v59, s17
	v_add3_u32 v39, v39, v62, s17
	v_add3_u32 v38, v38, v63, s17
	v_add3_u32 v52, v36, v71, s17
	v_add3_u32 v53, v37, v64, s17
	v_add3_u32 v35, v35, v76, s17
	v_add3_u32 v34, v34, v77, s17
	v_and_b32_e32 v36, 0xffff0000, v47
	v_and_b32_e32 v37, 0xffff0000, v46
	v_add3_u32 v44, v44, v57, s17
	v_add3_u32 v45, v45, v56, s17
	v_add3_u32 v40, v40, v61, s17
	v_add3_u32 v41, v41, v60, s17
	v_and_b32_e32 v43, 0xffff0000, v43
	v_and_b32_e32 v42, 0xffff0000, v42
	v_and_b32_e32 v39, 0xffff0000, v39
	v_and_b32_e32 v38, 0xffff0000, v38
	v_and_b32_e32 v46, 0xffff0000, v35
	v_and_b32_e32 v47, 0xffff0000, v34
	v_or_b32_sdwa v35, v36, v51 dst_sel:DWORD dst_unused:UNUSED_PAD src0_sel:DWORD src1_sel:WORD_1
	v_or_b32_sdwa v34, v37, v50 dst_sel:DWORD dst_unused:UNUSED_PAD src0_sel:DWORD src1_sel:WORD_1
	v_or_b32_sdwa v37, v43, v45 dst_sel:DWORD dst_unused:UNUSED_PAD src0_sel:DWORD src1_sel:WORD_1
	v_or_b32_sdwa v36, v42, v44 dst_sel:DWORD dst_unused:UNUSED_PAD src0_sel:DWORD src1_sel:WORD_1
	v_or_b32_sdwa v39, v39, v41 dst_sel:DWORD dst_unused:UNUSED_PAD src0_sel:DWORD src1_sel:WORD_1
	v_or_b32_sdwa v38, v38, v40 dst_sel:DWORD dst_unused:UNUSED_PAD src0_sel:DWORD src1_sel:WORD_1
	v_or_b32_sdwa v41, v46, v53 dst_sel:DWORD dst_unused:UNUSED_PAD src0_sel:DWORD src1_sel:WORD_1
	v_or_b32_sdwa v40, v47, v52 dst_sel:DWORD dst_unused:UNUSED_PAD src0_sel:DWORD src1_sel:WORD_1
	ds_write_b64 v180, v[34:35] offset:2048
	ds_write_b64 v181, v[36:37] offset:2048
	ds_write_b64 v182, v[38:39] offset:2048
	ds_write_b64 v183, v[40:41] offset:2048
	v_mov_b32_e32 v34, v175
	v_mov_b32_e32 v33, v30
	v_mov_b32_e32 v30, v29
	v_mov_b32_e32 v29, v26
	v_mov_b32_e32 v26, v25
	v_mov_b32_e32 v25, v22
	v_mov_b32_e32 v22, v21
	v_mov_b32_e32 v21, v18
	v_mov_b32_e32 v18, v17
	v_mov_b32_e32 v32, v28
	v_mov_b32_e32 v28, v24
	v_mov_b32_e32 v24, v20
	v_mov_b32_e32 v20, v16
	v_or_b32_e32 v16, 32, v70
	s_nop 0
	v_fmamk_f32 v17, v34, 0x3a800000, v102
	v_mul_f32_e32 v34, 0x4b800000, v17
	v_cmp_gt_f32_e32 vcc, s16, v17
	s_nop 1
	v_cndmask_b32_e32 v17, v17, v34, vcc
	v_rsq_f32_e32 v34, v17
	v_mad_i64_i32 v[16:17], s[8:9], v16, s15, v[72:73]
	v_lshl_add_u64 v[16:17], v[16:17], 0, v[48:49]
; DEVI unsigned pack2(float a, float b) { return (unsigned)f2bf(a) | ((unsigned)f2bf(b) << 16); }
; DEVI void phase_scaled(const Params& p, unsigned char* smem, const u16* A, const u16* Wt, int ntn, const float* ssq, u16* outp, int ldo) {
;     ...
; #pragma unroll
;     for (int mi = 0; mi < 4; ++mi) {
;       const int m = m0 + wm * 64 + 16 * mi + col;
;       const float rstd = rsqrtf(ssq[m] * (1.f / D) + 1e-6f);
; #pragma unroll
;       for (int ni = 0; ni < 4; ++ni) {
;         const int n = n0 + wn * 64 + 16 * ni + 4 * quad;
;         const f32x4 v = acc[ni][mi];
;         uint2 pk; pk.x = pack2(v[0] * rstd, v[1] * rstd); pk.y = pack2(v[2] * rstd, v[3] * rstd);
;         *(uint2*)(outp + (size_t)m * ldo + n) = pk;
;       }
;     }
	v_mul_f32_e32 v35, 0x45800000, v34
	v_cndmask_b32_e32 v34, v34, v35, vcc
	v_pk_mul_f32 v[30:31], v[30:31], v[34:35] op_sel_hi:[1,0]
	v_pk_mul_f32 v[32:33], v[32:33], v[34:35] op_sel_hi:[1,0]
	v_pk_mul_f32 v[26:27], v[26:27], v[34:35] op_sel_hi:[1,0]
	v_pk_mul_f32 v[22:23], v[22:23], v[34:35] op_sel_hi:[1,0]
	v_pk_mul_f32 v[20:21], v[20:21], v[34:35] op_sel_hi:[1,0]
	v_pk_mul_f32 v[18:19], v[18:19], v[34:35] op_sel_hi:[1,0]
	v_and_b32_sdwa v36, v31, v103 dst_sel:DWORD dst_unused:UNUSED_PAD src0_sel:WORD_1 src1_sel:DWORD
	v_and_b32_sdwa v37, v30, v103 dst_sel:DWORD dst_unused:UNUSED_PAD src0_sel:WORD_1 src1_sel:DWORD
	v_pk_mul_f32 v[28:29], v[28:29], v[34:35] op_sel_hi:[1,0]
	v_pk_mul_f32 v[24:25], v[24:25], v[34:35] op_sel_hi:[1,0]
	v_and_b32_sdwa v34, v33, v103 dst_sel:DWORD dst_unused:UNUSED_PAD src0_sel:WORD_1 src1_sel:DWORD
	v_and_b32_sdwa v35, v32, v103 dst_sel:DWORD dst_unused:UNUSED_PAD src0_sel:WORD_1 src1_sel:DWORD
	v_and_b32_sdwa v40, v27, v103 dst_sel:DWORD dst_unused:UNUSED_PAD src0_sel:WORD_1 src1_sel:DWORD
	v_and_b32_sdwa v41, v26, v103 dst_sel:DWORD dst_unused:UNUSED_PAD src0_sel:WORD_1 src1_sel:DWORD
	v_and_b32_sdwa v44, v23, v103 dst_sel:DWORD dst_unused:UNUSED_PAD src0_sel:WORD_1 src1_sel:DWORD
	v_and_b32_sdwa v45, v22, v103 dst_sel:DWORD dst_unused:UNUSED_PAD src0_sel:WORD_1 src1_sel:DWORD
	v_and_b32_sdwa v46, v21, v103 dst_sel:DWORD dst_unused:UNUSED_PAD src0_sel:WORD_1 src1_sel:DWORD
	v_and_b32_sdwa v47, v20, v103 dst_sel:DWORD dst_unused:UNUSED_PAD src0_sel:WORD_1 src1_sel:DWORD
	v_and_b32_sdwa v50, v19, v103 dst_sel:DWORD dst_unused:UNUSED_PAD src0_sel:WORD_1 src1_sel:DWORD
	v_and_b32_sdwa v51, v18, v103 dst_sel:DWORD dst_unused:UNUSED_PAD src0_sel:WORD_1 src1_sel:DWORD
	v_add3_u32 v31, v31, v36, s17
	v_add3_u32 v30, v30, v37, s17
	v_and_b32_sdwa v38, v29, v103 dst_sel:DWORD dst_unused:UNUSED_PAD src0_sel:WORD_1 src1_sel:DWORD
	v_and_b32_sdwa v39, v28, v103 dst_sel:DWORD dst_unused:UNUSED_PAD src0_sel:WORD_1 src1_sel:DWORD
	v_and_b32_sdwa v42, v25, v103 dst_sel:DWORD dst_unused:UNUSED_PAD src0_sel:WORD_1 src1_sel:DWORD
	v_and_b32_sdwa v43, v24, v103 dst_sel:DWORD dst_unused:UNUSED_PAD src0_sel:WORD_1 src1_sel:DWORD
	v_add3_u32 v32, v32, v35, s17
	v_add3_u32 v33, v33, v34, s17
	v_add3_u32 v27, v27, v40, s17
	v_add3_u32 v26, v26, v41, s17
	v_add3_u32 v23, v23, v44, s17
	v_add3_u32 v22, v22, v45, s17
	v_add3_u32 v34, v20, v47, s17
	v_add3_u32 v35, v21, v46, s17
	v_add3_u32 v19, v19, v50, s17
	v_add3_u32 v18, v18, v51, s17
	v_and_b32_e32 v20, 0xffff0000, v31
	v_and_b32_e32 v21, 0xffff0000, v30
	v_add3_u32 v28, v28, v39, s17
	v_add3_u32 v29, v29, v38, s17
	v_add3_u32 v24, v24, v43, s17
	v_add3_u32 v25, v25, v42, s17
	v_and_b32_e32 v27, 0xffff0000, v27
	v_and_b32_e32 v26, 0xffff0000, v26
	v_and_b32_e32 v23, 0xffff0000, v23
	v_and_b32_e32 v22, 0xffff0000, v22
	v_and_b32_e32 v30, 0xffff0000, v19
	v_and_b32_e32 v31, 0xffff0000, v18
	v_or_b32_sdwa v19, v20, v33 dst_sel:DWORD dst_unused:UNUSED_PAD src0_sel:DWORD src1_sel:WORD_1
	v_or_b32_sdwa v18, v21, v32 dst_sel:DWORD dst_unused:UNUSED_PAD src0_sel:DWORD src1_sel:WORD_1
	v_or_b32_sdwa v21, v27, v29 dst_sel:DWORD dst_unused:UNUSED_PAD src0_sel:DWORD src1_sel:WORD_1
	v_or_b32_sdwa v20, v26, v28 dst_sel:DWORD dst_unused:UNUSED_PAD src0_sel:DWORD src1_sel:WORD_1
	v_or_b32_sdwa v23, v23, v25 dst_sel:DWORD dst_unused:UNUSED_PAD src0_sel:DWORD src1_sel:WORD_1
	v_or_b32_sdwa v22, v22, v24 dst_sel:DWORD dst_unused:UNUSED_PAD src0_sel:DWORD src1_sel:WORD_1
	v_or_b32_sdwa v25, v30, v35 dst_sel:DWORD dst_unused:UNUSED_PAD src0_sel:DWORD src1_sel:WORD_1
	v_or_b32_sdwa v24, v31, v34 dst_sel:DWORD dst_unused:UNUSED_PAD src0_sel:DWORD src1_sel:WORD_1
	ds_write_b64 v180, v[18:19] offset:4096
	ds_write_b64 v181, v[20:21] offset:4096
	ds_write_b64 v182, v[22:23] offset:4096
	ds_write_b64 v183, v[24:25] offset:4096
	v_mov_b32_e32 v18, v176
	v_mov_b32_e32 v17, v14
	v_mov_b32_e32 v14, v13
	v_mov_b32_e32 v13, v10
	v_mov_b32_e32 v10, v9
	v_mov_b32_e32 v9, v6
	v_mov_b32_e32 v6, v5
	v_mov_b32_e32 v5, v2
	v_mov_b32_e32 v2, v1
	v_mov_b32_e32 v16, v12
	v_mov_b32_e32 v12, v8
	v_mov_b32_e32 v8, v4
	v_mov_b32_e32 v4, v0
	v_or_b32_e32 v0, 48, v70
	s_nop 0
	v_fmamk_f32 v1, v18, 0x3a800000, v102
	v_mul_f32_e32 v18, 0x4b800000, v1
	v_cmp_gt_f32_e32 vcc, s16, v1
	s_nop 1
	v_cndmask_b32_e32 v1, v1, v18, vcc
	v_rsq_f32_e32 v18, v1
	v_mad_i64_i32 v[0:1], s[8:9], v0, s15, v[72:73]
	v_lshl_add_u64 v[0:1], v[0:1], 0, v[48:49]
	v_mul_f32_e32 v19, 0x45800000, v18
	v_cndmask_b32_e32 v18, v18, v19, vcc
	v_pk_mul_f32 v[14:15], v[14:15], v[18:19] op_sel_hi:[1,0]
	v_pk_mul_f32 v[16:17], v[16:17], v[18:19] op_sel_hi:[1,0]
	v_pk_mul_f32 v[10:11], v[10:11], v[18:19] op_sel_hi:[1,0]
; DEVI unsigned pack2(float a, float b) { return (unsigned)f2bf(a) | ((unsigned)f2bf(b) << 16); }
; DEVI void phase_scaled(const Params& p, unsigned char* smem, const u16* A, const u16* Wt, int ntn, const float* ssq, u16* outp, int ldo) {
;     ...
; #pragma unroll
;     for (int mi = 0; mi < 4; ++mi) {
;       const int m = m0 + wm * 64 + 16 * mi + col;
;       const float rstd = rsqrtf(ssq[m] * (1.f / D) + 1e-6f);
; #pragma unroll
;       for (int ni = 0; ni < 4; ++ni) {
;         const int n = n0 + wn * 64 + 16 * ni + 4 * quad;
;         const f32x4 v = acc[ni][mi];
;         uint2 pk; pk.x = pack2(v[0] * rstd, v[1] * rstd); pk.y = pack2(v[2] * rstd, v[3] * rstd);
;         *(uint2*)(outp + (size_t)m * ldo + n) = pk;
;       }
;     }
	v_pk_mul_f32 v[6:7], v[6:7], v[18:19] op_sel_hi:[1,0]
	v_pk_mul_f32 v[4:5], v[4:5], v[18:19] op_sel_hi:[1,0]
	v_pk_mul_f32 v[2:3], v[2:3], v[18:19] op_sel_hi:[1,0]
	v_and_b32_sdwa v20, v15, v103 dst_sel:DWORD dst_unused:UNUSED_PAD src0_sel:WORD_1 src1_sel:DWORD
	v_and_b32_sdwa v21, v14, v103 dst_sel:DWORD dst_unused:UNUSED_PAD src0_sel:WORD_1 src1_sel:DWORD
	v_pk_mul_f32 v[12:13], v[12:13], v[18:19] op_sel_hi:[1,0]
	v_pk_mul_f32 v[8:9], v[8:9], v[18:19] op_sel_hi:[1,0]
	v_and_b32_sdwa v18, v17, v103 dst_sel:DWORD dst_unused:UNUSED_PAD src0_sel:WORD_1 src1_sel:DWORD
	v_and_b32_sdwa v19, v16, v103 dst_sel:DWORD dst_unused:UNUSED_PAD src0_sel:WORD_1 src1_sel:DWORD
	v_and_b32_sdwa v24, v11, v103 dst_sel:DWORD dst_unused:UNUSED_PAD src0_sel:WORD_1 src1_sel:DWORD
	v_and_b32_sdwa v25, v10, v103 dst_sel:DWORD dst_unused:UNUSED_PAD src0_sel:WORD_1 src1_sel:DWORD
	v_and_b32_sdwa v28, v7, v103 dst_sel:DWORD dst_unused:UNUSED_PAD src0_sel:WORD_1 src1_sel:DWORD
	v_and_b32_sdwa v29, v6, v103 dst_sel:DWORD dst_unused:UNUSED_PAD src0_sel:WORD_1 src1_sel:DWORD
	v_and_b32_sdwa v30, v5, v103 dst_sel:DWORD dst_unused:UNUSED_PAD src0_sel:WORD_1 src1_sel:DWORD
	v_and_b32_sdwa v31, v4, v103 dst_sel:DWORD dst_unused:UNUSED_PAD src0_sel:WORD_1 src1_sel:DWORD
	v_and_b32_sdwa v32, v3, v103 dst_sel:DWORD dst_unused:UNUSED_PAD src0_sel:WORD_1 src1_sel:DWORD
	v_and_b32_sdwa v33, v2, v103 dst_sel:DWORD dst_unused:UNUSED_PAD src0_sel:WORD_1 src1_sel:DWORD
	v_add3_u32 v15, v15, v20, s17
	v_add3_u32 v14, v14, v21, s17
	v_and_b32_sdwa v22, v13, v103 dst_sel:DWORD dst_unused:UNUSED_PAD src0_sel:WORD_1 src1_sel:DWORD
	v_and_b32_sdwa v23, v12, v103 dst_sel:DWORD dst_unused:UNUSED_PAD src0_sel:WORD_1 src1_sel:DWORD
	v_and_b32_sdwa v26, v9, v103 dst_sel:DWORD dst_unused:UNUSED_PAD src0_sel:WORD_1 src1_sel:DWORD
	v_and_b32_sdwa v27, v8, v103 dst_sel:DWORD dst_unused:UNUSED_PAD src0_sel:WORD_1 src1_sel:DWORD
	v_add3_u32 v16, v16, v19, s17
	v_add3_u32 v17, v17, v18, s17
	v_add3_u32 v11, v11, v24, s17
	v_add3_u32 v10, v10, v25, s17
	v_add3_u32 v7, v7, v28, s17
	v_add3_u32 v6, v6, v29, s17
	v_add3_u32 v18, v4, v31, s17
	v_add3_u32 v19, v5, v30, s17
	v_add3_u32 v3, v3, v32, s17
	v_add3_u32 v2, v2, v33, s17
	v_and_b32_e32 v4, 0xffff0000, v15
	v_and_b32_e32 v5, 0xffff0000, v14
	v_add3_u32 v12, v12, v23, s17
	v_add3_u32 v13, v13, v22, s17
	v_add3_u32 v8, v8, v27, s17
	v_add3_u32 v9, v9, v26, s17
	v_and_b32_e32 v11, 0xffff0000, v11
	v_and_b32_e32 v10, 0xffff0000, v10
	v_and_b32_e32 v7, 0xffff0000, v7
	v_and_b32_e32 v6, 0xffff0000, v6
	v_and_b32_e32 v14, 0xffff0000, v3
	v_and_b32_e32 v15, 0xffff0000, v2
	v_or_b32_sdwa v3, v4, v17 dst_sel:DWORD dst_unused:UNUSED_PAD src0_sel:DWORD src1_sel:WORD_1
	v_or_b32_sdwa v2, v5, v16 dst_sel:DWORD dst_unused:UNUSED_PAD src0_sel:DWORD src1_sel:WORD_1
	v_or_b32_sdwa v5, v11, v13 dst_sel:DWORD dst_unused:UNUSED_PAD src0_sel:DWORD src1_sel:WORD_1
	v_or_b32_sdwa v4, v10, v12 dst_sel:DWORD dst_unused:UNUSED_PAD src0_sel:DWORD src1_sel:WORD_1
	v_or_b32_sdwa v7, v7, v9 dst_sel:DWORD dst_unused:UNUSED_PAD src0_sel:DWORD src1_sel:WORD_1
	v_or_b32_sdwa v6, v6, v8 dst_sel:DWORD dst_unused:UNUSED_PAD src0_sel:DWORD src1_sel:WORD_1
	v_or_b32_sdwa v9, v14, v19 dst_sel:DWORD dst_unused:UNUSED_PAD src0_sel:DWORD src1_sel:WORD_1
	v_or_b32_sdwa v8, v15, v18 dst_sel:DWORD dst_unused:UNUSED_PAD src0_sel:DWORD src1_sel:WORD_1
	ds_write_b64 v180, v[2:3] offset:6144
	ds_write_b64 v181, v[4:5] offset:6144
	ds_write_b64 v182, v[6:7] offset:6144
	ds_write_b64 v183, v[8:9] offset:6144
	s_waitcnt lgkmcnt(0)
	ds_read_b128 v[212:215], v184 offset:0
	ds_read_b128 v[216:219], v184 offset:1024
	ds_read_b128 v[220:223], v184 offset:2048
	ds_read_b128 v[224:227], v184 offset:3072
	ds_read_b128 v[228:231], v184 offset:4096
	ds_read_b128 v[232:235], v184 offset:5120
	ds_read_b128 v[236:239], v184 offset:6144
	ds_read_b128 v[240:243], v184 offset:7168
	s_waitcnt lgkmcnt(7)
	global_store_dwordx4 v185, v[212:215], s[98:99]
	v_add_u32_e32 v185, v185, v186
	s_waitcnt lgkmcnt(6)
	global_store_dwordx4 v185, v[216:219], s[98:99]
	v_add_u32_e32 v185, v185, v186
	s_waitcnt lgkmcnt(5)
	global_store_dwordx4 v185, v[220:223], s[98:99]
	v_add_u32_e32 v185, v185, v186
	s_waitcnt lgkmcnt(4)
	global_store_dwordx4 v185, v[224:227], s[98:99]
	v_add_u32_e32 v185, v185, v186
	s_waitcnt lgkmcnt(3)
	global_store_dwordx4 v185, v[228:231], s[98:99]
	v_add_u32_e32 v185, v185, v186
	s_waitcnt lgkmcnt(2)
	global_store_dwordx4 v185, v[232:235], s[98:99]
	v_add_u32_e32 v185, v185, v186
	s_waitcnt lgkmcnt(1)
	global_store_dwordx4 v185, v[236:239], s[98:99]
	v_add_u32_e32 v185, v185, v186
	s_waitcnt lgkmcnt(0)
	global_store_dwordx4 v185, v[240:243], s[98:99]
	s_barrier
	s_cbranch_scc0 .LBB0_966

; DEVI unsigned pack2(float a, float b) { return (unsigned)f2bf(a) | ((unsigned)f2bf(b) << 16); }
; DEVI void phase_scaled(const Params& p, unsigned char* smem, const u16* A, const u16* Wt, int ntn, const float* ssq, u16* outp, int ldo) {
;     ...
; #pragma unroll
;     for (int mi = 0; mi < 4; ++mi) {
;       const int m = m0 + wm * 64 + 16 * mi + col;
;       const float rstd = rsqrtf(ssq[m] * (1.f / D) + 1e-6f);
; #pragma unroll
;       for (int ni = 0; ni < 4; ++ni) {
;         const int n = n0 + wn * 64 + 16 * ni + 4 * quad;
;         const f32x4 v = acc[ni][mi];
;         uint2 pk; pk.x = pack2(v[0] * rstd, v[1] * rstd); pk.y = pack2(v[2] * rstd, v[3] * rstd);
;         *(uint2*)(outp + (size_t)m * ldo + n) = pk;
;       }
;     }
.LBB0_1158:
	v_and_b32_e32 v200, 63, v210
	v_lshrrev_b32_e32 v201, 6, v210
	v_and_b32_e32 v202, 15, v200
	v_lshrrev_b32_e32 v203, 4, v200
	v_lshlrev_b32_e32 v204, 13, v201
	v_lshl_add_u32 v204, v202, 7, v204
	v_and_b32_e32 v205, 1, v203
	v_lshl_add_u32 v204, v205, 3, v204
	v_lshrrev_b32_e32 v205, 1, v203
	v_and_b32_e32 v206, 7, v202
	v_xor_b32_e32 v205, v205, v206
	v_xor_b32_e32 v207, 0, v205
	v_lshl_add_u32 v180, v207, 4, v204
	v_xor_b32_e32 v207, 2, v205
	v_lshl_add_u32 v181, v207, 4, v204
	v_xor_b32_e32 v207, 4, v205
	v_lshl_add_u32 v182, v207, 4, v204
	v_xor_b32_e32 v207, 6, v205
	v_lshl_add_u32 v183, v207, 4, v204
	v_lshrrev_b32_e32 v206, 3, v200
	v_and_b32_e32 v207, 7, v200
	v_lshlrev_b32_e32 v184, 13, v201
	v_lshl_add_u32 v184, v206, 7, v184
	v_lshl_add_u32 v184, v207, 4, v184
	v_xor_b32_e32 v207, v207, v206
	v_lshlrev_b32_e32 v207, 4, v207
	v_mul_lo_u32 v185, v206, s17
	v_add_u32_e32 v185, v185, v207
	v_mov_b32_e32 v186, s17
	v_lshlrev_b32_e32 v186, 3, v186
	v_ashrrev_i32_e32 v64, 1, v104
	v_and_b32_e32 v64, 0xffffffc0, v64
	v_add_u32_e32 v64, s20, v64
	v_and_or_b32 v70, v104, 15, v64
	v_ashrrev_i32_e32 v71, 31, v70
	v_lshl_add_u64 v[74:75], v[70:71], 2, s[50:51]
	global_load_dword v64, v[74:75], off
	global_load_dword v174, v[74:75], off offset:64
	global_load_dword v175, v[74:75], off offset:128
	global_load_dword v176, v[74:75], off offset:192
	v_lshrrev_b32_e32 v78, 2, v104
	v_and_b32_e32 v71, 64, v104
	v_mov_b32_e32 v76, v60
	v_mov_b32_e32 v60, v56
	v_mov_b32_e32 v56, v52
	v_mov_b32_e32 v52, v48
	v_and_b32_e32 v48, 12, v78
	v_or3_b32 v48, v71, v48, s19
	v_mov_b32_e32 v77, v62
	v_mov_b32_e32 v62, v61
	v_readlane_b32 s20, v248, 12
	v_mov_b32_e32 v61, v58
	v_mov_b32_e32 v58, v57
	v_mov_b32_e32 v57, v54
	v_mov_b32_e32 v54, v53
	v_mov_b32_e32 v53, v50
	v_mov_b32_e32 v50, v49
	v_readlane_b32 s22, v248, 14
	v_readlane_b32 s23, v248, 15
	v_ashrrev_i32_e32 v49, 31, v48
	v_lshlrev_b64 v[48:49], 1, v[48:49]
	v_mov_b64_e32 v[72:73], s[22:23]
	v_mad_i64_i32 v[78:79], s[8:9], v70, s17, v[72:73]
	v_lshl_add_u64 v[78:79], v[78:79], 0, v[48:49]
	s_add_i32 s11, s11, s14
	s_cmp_lt_i32 s11, s12
	v_readlane_b32 s21, v248, 13
	s_waitcnt vmcnt(0)
	v_fmamk_f32 v64, v64, 0x3a800000, v102
	v_mul_f32_e32 v71, 0x4b800000, v64
	v_cmp_gt_f32_e32 vcc, s16, v64
	s_nop 1
	v_cndmask_b32_e32 v64, v64, v71, vcc
	v_rsq_f32_e32 v64, v64
	s_nop 0
	v_mul_f32_e32 v71, 0x45800000, v64
	v_cndmask_b32_e32 v64, v64, v71, vcc
	v_pk_mul_f32 v[62:63], v[62:63], v[64:65] op_sel_hi:[1,0]
	v_pk_mul_f32 v[76:77], v[76:77], v[64:65] op_sel_hi:[1,0]
	v_pk_mul_f32 v[58:59], v[58:59], v[64:65] op_sel_hi:[1,0]
	v_pk_mul_f32 v[54:55], v[54:55], v[64:65] op_sel_hi:[1,0]
	v_pk_mul_f32 v[52:53], v[52:53], v[64:65] op_sel_hi:[1,0]
	v_pk_mul_f32 v[50:51], v[50:51], v[64:65] op_sel_hi:[1,0]
	v_and_b32_sdwa v80, v63, v103 dst_sel:DWORD dst_unused:UNUSED_PAD src0_sel:WORD_1 src1_sel:DWORD
	v_and_b32_sdwa v81, v62, v103 dst_sel:DWORD dst_unused:UNUSED_PAD src0_sel:WORD_1 src1_sel:DWORD
	v_pk_mul_f32 v[60:61], v[60:61], v[64:65] op_sel_hi:[1,0]
	v_pk_mul_f32 v[56:57], v[56:57], v[64:65] op_sel_hi:[1,0]
	v_and_b32_sdwa v64, v77, v103 dst_sel:DWORD dst_unused:UNUSED_PAD src0_sel:WORD_1 src1_sel:DWORD
	v_and_b32_sdwa v71, v76, v103 dst_sel:DWORD dst_unused:UNUSED_PAD src0_sel:WORD_1 src1_sel:DWORD
	v_and_b32_sdwa v84, v59, v103 dst_sel:DWORD dst_unused:UNUSED_PAD src0_sel:WORD_1 src1_sel:DWORD
	v_and_b32_sdwa v85, v58, v103 dst_sel:DWORD dst_unused:UNUSED_PAD src0_sel:WORD_1 src1_sel:DWORD
	v_and_b32_sdwa v88, v55, v103 dst_sel:DWORD dst_unused:UNUSED_PAD src0_sel:WORD_1 src1_sel:DWORD
	v_and_b32_sdwa v89, v54, v103 dst_sel:DWORD dst_unused:UNUSED_PAD src0_sel:WORD_1 src1_sel:DWORD
	v_and_b32_sdwa v90, v53, v103 dst_sel:DWORD dst_unused:UNUSED_PAD src0_sel:WORD_1 src1_sel:DWORD
	v_and_b32_sdwa v91, v52, v103 dst_sel:DWORD dst_unused:UNUSED_PAD src0_sel:WORD_1 src1_sel:DWORD
	v_and_b32_sdwa v92, v51, v103 dst_sel:DWORD dst_unused:UNUSED_PAD src0_sel:WORD_1 src1_sel:DWORD
	v_and_b32_sdwa v93, v50, v103 dst_sel:DWORD dst_unused:UNUSED_PAD src0_sel:WORD_1 src1_sel:DWORD
	v_add3_u32 v63, v63, v80, s18
	v_add3_u32 v62, v62, v81, s18
	v_and_b32_sdwa v82, v61, v103 dst_sel:DWORD dst_unused:UNUSED_PAD src0_sel:WORD_1 src1_sel:DWORD
	v_and_b32_sdwa v83, v60, v103 dst_sel:DWORD dst_unused:UNUSED_PAD src0_sel:WORD_1 src1_sel:DWORD
	v_and_b32_sdwa v86, v57, v103 dst_sel:DWORD dst_unused:UNUSED_PAD src0_sel:WORD_1 src1_sel:DWORD
	v_and_b32_sdwa v87, v56, v103 dst_sel:DWORD dst_unused:UNUSED_PAD src0_sel:WORD_1 src1_sel:DWORD
	v_add3_u32 v71, v76, v71, s18
	v_add3_u32 v64, v77, v64, s18
	v_add3_u32 v59, v59, v84, s18
	v_add3_u32 v58, v58, v85, s18
	v_add3_u32 v55, v55, v88, s18
	v_add3_u32 v54, v54, v89, s18
	v_add3_u32 v76, v52, v91, s18
	v_add3_u32 v77, v53, v90, s18
	v_add3_u32 v51, v51, v92, s18
	v_add3_u32 v50, v50, v93, s18
	v_and_b32_e32 v52, 0xffff0000, v63
	v_and_b32_e32 v53, 0xffff0000, v62
	v_add3_u32 v60, v60, v83, s18
	v_add3_u32 v61, v61, v82, s18
	v_add3_u32 v56, v56, v87, s18
	v_add3_u32 v57, v57, v86, s18
	v_and_b32_e32 v59, 0xffff0000, v59
	v_and_b32_e32 v58, 0xffff0000, v58
	v_and_b32_e32 v55, 0xffff0000, v55
	v_and_b32_e32 v54, 0xffff0000, v54
	v_and_b32_e32 v62, 0xffff0000, v51
	v_and_b32_e32 v63, 0xffff0000, v50
	v_or_b32_sdwa v51, v52, v64 dst_sel:DWORD dst_unused:UNUSED_PAD src0_sel:DWORD src1_sel:WORD_1
	v_or_b32_sdwa v50, v53, v71 dst_sel:DWORD dst_unused:UNUSED_PAD src0_sel:DWORD src1_sel:WORD_1
	v_or_b32_sdwa v53, v59, v61 dst_sel:DWORD dst_unused:UNUSED_PAD src0_sel:DWORD src1_sel:WORD_1
	v_or_b32_sdwa v52, v58, v60 dst_sel:DWORD dst_unused:UNUSED_PAD src0_sel:DWORD src1_sel:WORD_1
; DEVI unsigned pack2(float a, float b) { return (unsigned)f2bf(a) | ((unsigned)f2bf(b) << 16); }
; DEVI void phase_scaled(const Params& p, unsigned char* smem, const u16* A, const u16* Wt, int ntn, const float* ssq, u16* outp, int ldo) {
;     ...
; #pragma unroll
;     for (int mi = 0; mi < 4; ++mi) {
;       const int m = m0 + wm * 64 + 16 * mi + col;
;       const float rstd = rsqrtf(ssq[m] * (1.f / D) + 1e-6f);
; #pragma unroll
;       for (int ni = 0; ni < 4; ++ni) {
;         const int n = n0 + wn * 64 + 16 * ni + 4 * quad;
;         const f32x4 v = acc[ni][mi];
;         uint2 pk; pk.x = pack2(v[0] * rstd, v[1] * rstd); pk.y = pack2(v[2] * rstd, v[3] * rstd);
;         *(uint2*)(outp + (size_t)m * ldo + n) = pk;
;       }
;     }
	v_or_b32_sdwa v55, v55, v57 dst_sel:DWORD dst_unused:UNUSED_PAD src0_sel:DWORD src1_sel:WORD_1
	v_or_b32_sdwa v54, v54, v56 dst_sel:DWORD dst_unused:UNUSED_PAD src0_sel:DWORD src1_sel:WORD_1
	v_or_b32_sdwa v57, v62, v77 dst_sel:DWORD dst_unused:UNUSED_PAD src0_sel:DWORD src1_sel:WORD_1
	v_or_b32_sdwa v56, v63, v76 dst_sel:DWORD dst_unused:UNUSED_PAD src0_sel:DWORD src1_sel:WORD_1
	v_readfirstlane_b32 s98, v78
	v_readfirstlane_b32 s99, v79
	ds_write_b64 v180, v[50:51]
	ds_write_b64 v181, v[52:53]
	ds_write_b64 v182, v[54:55]
	ds_write_b64 v183, v[56:57]
	v_mov_b32_e32 v52, v174
	v_mov_b32_e32 v51, v46
	v_mov_b32_e32 v46, v45
	v_mov_b32_e32 v45, v42
	v_mov_b32_e32 v42, v41
	v_mov_b32_e32 v41, v38
	v_mov_b32_e32 v38, v37
	v_mov_b32_e32 v37, v34
	v_mov_b32_e32 v34, v33
	v_mov_b32_e32 v50, v44
	v_mov_b32_e32 v44, v40
	v_mov_b32_e32 v40, v36
	v_mov_b32_e32 v36, v32
	v_or_b32_e32 v32, 16, v70
	s_nop 0
	v_fmamk_f32 v33, v52, 0x3a800000, v102
	v_mul_f32_e32 v52, 0x4b800000, v33
	v_cmp_gt_f32_e32 vcc, s16, v33
	s_nop 1
	v_cndmask_b32_e32 v33, v33, v52, vcc
	v_rsq_f32_e32 v52, v33
	v_mad_i64_i32 v[32:33], s[8:9], v32, s17, v[72:73]
	v_lshl_add_u64 v[32:33], v[32:33], 0, v[48:49]
	v_mul_f32_e32 v53, 0x45800000, v52
	v_cndmask_b32_e32 v52, v52, v53, vcc
	v_pk_mul_f32 v[46:47], v[46:47], v[52:53] op_sel_hi:[1,0]
	v_pk_mul_f32 v[50:51], v[50:51], v[52:53] op_sel_hi:[1,0]
	v_pk_mul_f32 v[42:43], v[42:43], v[52:53] op_sel_hi:[1,0]
	v_pk_mul_f32 v[38:39], v[38:39], v[52:53] op_sel_hi:[1,0]
	v_pk_mul_f32 v[36:37], v[36:37], v[52:53] op_sel_hi:[1,0]
	v_pk_mul_f32 v[34:35], v[34:35], v[52:53] op_sel_hi:[1,0]
	v_and_b32_sdwa v54, v47, v103 dst_sel:DWORD dst_unused:UNUSED_PAD src0_sel:WORD_1 src1_sel:DWORD
	v_and_b32_sdwa v55, v46, v103 dst_sel:DWORD dst_unused:UNUSED_PAD src0_sel:WORD_1 src1_sel:DWORD
	v_pk_mul_f32 v[44:45], v[44:45], v[52:53] op_sel_hi:[1,0]
	v_pk_mul_f32 v[40:41], v[40:41], v[52:53] op_sel_hi:[1,0]
	v_and_b32_sdwa v52, v51, v103 dst_sel:DWORD dst_unused:UNUSED_PAD src0_sel:WORD_1 src1_sel:DWORD
	v_and_b32_sdwa v53, v50, v103 dst_sel:DWORD dst_unused:UNUSED_PAD src0_sel:WORD_1 src1_sel:DWORD
	v_and_b32_sdwa v58, v43, v103 dst_sel:DWORD dst_unused:UNUSED_PAD src0_sel:WORD_1 src1_sel:DWORD
	v_and_b32_sdwa v59, v42, v103 dst_sel:DWORD dst_unused:UNUSED_PAD src0_sel:WORD_1 src1_sel:DWORD
	v_and_b32_sdwa v62, v39, v103 dst_sel:DWORD dst_unused:UNUSED_PAD src0_sel:WORD_1 src1_sel:DWORD
	v_and_b32_sdwa v63, v38, v103 dst_sel:DWORD dst_unused:UNUSED_PAD src0_sel:WORD_1 src1_sel:DWORD
	v_and_b32_sdwa v64, v37, v103 dst_sel:DWORD dst_unused:UNUSED_PAD src0_sel:WORD_1 src1_sel:DWORD
	v_and_b32_sdwa v71, v36, v103 dst_sel:DWORD dst_unused:UNUSED_PAD src0_sel:WORD_1 src1_sel:DWORD
	v_and_b32_sdwa v76, v35, v103 dst_sel:DWORD dst_unused:UNUSED_PAD src0_sel:WORD_1 src1_sel:DWORD
	v_and_b32_sdwa v77, v34, v103 dst_sel:DWORD dst_unused:UNUSED_PAD src0_sel:WORD_1 src1_sel:DWORD
	v_add3_u32 v47, v47, v54, s18
	v_add3_u32 v46, v46, v55, s18
	v_and_b32_sdwa v56, v45, v103 dst_sel:DWORD dst_unused:UNUSED_PAD src0_sel:WORD_1 src1_sel:DWORD
	v_and_b32_sdwa v57, v44, v103 dst_sel:DWORD dst_unused:UNUSED_PAD src0_sel:WORD_1 src1_sel:DWORD
	v_and_b32_sdwa v60, v41, v103 dst_sel:DWORD dst_unused:UNUSED_PAD src0_sel:WORD_1 src1_sel:DWORD
	v_and_b32_sdwa v61, v40, v103 dst_sel:DWORD dst_unused:UNUSED_PAD src0_sel:WORD_1 src1_sel:DWORD
	v_add3_u32 v50, v50, v53, s18
	v_add3_u32 v51, v51, v52, s18
	v_add3_u32 v43, v43, v58, s18
	v_add3_u32 v42, v42, v59, s18
	v_add3_u32 v39, v39, v62, s18
	v_add3_u32 v38, v38, v63, s18
	v_add3_u32 v52, v36, v71, s18
	v_add3_u32 v53, v37, v64, s18
	v_add3_u32 v35, v35, v76, s18
	v_add3_u32 v34, v34, v77, s18
	v_and_b32_e32 v36, 0xffff0000, v47
	v_and_b32_e32 v37, 0xffff0000, v46
	v_add3_u32 v44, v44, v57, s18
	v_add3_u32 v45, v45, v56, s18
	v_add3_u32 v40, v40, v61, s18
	v_add3_u32 v41, v41, v60, s18
	v_and_b32_e32 v43, 0xffff0000, v43
	v_and_b32_e32 v42, 0xffff0000, v42
	v_and_b32_e32 v39, 0xffff0000, v39
	v_and_b32_e32 v38, 0xffff0000, v38
	v_and_b32_e32 v46, 0xffff0000, v35
	v_and_b32_e32 v47, 0xffff0000, v34
	v_or_b32_sdwa v35, v36, v51 dst_sel:DWORD dst_unused:UNUSED_PAD src0_sel:DWORD src1_sel:WORD_1
	v_or_b32_sdwa v34, v37, v50 dst_sel:DWORD dst_unused:UNUSED_PAD src0_sel:DWORD src1_sel:WORD_1
	v_or_b32_sdwa v37, v43, v45 dst_sel:DWORD dst_unused:UNUSED_PAD src0_sel:DWORD src1_sel:WORD_1
	v_or_b32_sdwa v36, v42, v44 dst_sel:DWORD dst_unused:UNUSED_PAD src0_sel:DWORD src1_sel:WORD_1
	v_or_b32_sdwa v39, v39, v41 dst_sel:DWORD dst_unused:UNUSED_PAD src0_sel:DWORD src1_sel:WORD_1
	v_or_b32_sdwa v38, v38, v40 dst_sel:DWORD dst_unused:UNUSED_PAD src0_sel:DWORD src1_sel:WORD_1
	v_or_b32_sdwa v41, v46, v53 dst_sel:DWORD dst_unused:UNUSED_PAD src0_sel:DWORD src1_sel:WORD_1
	v_or_b32_sdwa v40, v47, v52 dst_sel:DWORD dst_unused:UNUSED_PAD src0_sel:DWORD src1_sel:WORD_1
	ds_write_b64 v180, v[34:35] offset:2048
	ds_write_b64 v181, v[36:37] offset:2048
	ds_write_b64 v182, v[38:39] offset:2048
	ds_write_b64 v183, v[40:41] offset:2048
	v_mov_b32_e32 v34, v175
	v_mov_b32_e32 v33, v30
	v_mov_b32_e32 v30, v29
	v_mov_b32_e32 v29, v26
	v_mov_b32_e32 v26, v25
	v_mov_b32_e32 v25, v22
	v_mov_b32_e32 v22, v21
	v_mov_b32_e32 v21, v18
	v_mov_b32_e32 v18, v17
	v_mov_b32_e32 v32, v28
	v_mov_b32_e32 v28, v24
	v_mov_b32_e32 v24, v20
	v_mov_b32_e32 v20, v16
	v_or_b32_e32 v16, 32, v70
	s_nop 0
	v_fmamk_f32 v17, v34, 0x3a800000, v102
	v_mul_f32_e32 v34, 0x4b800000, v17
	v_cmp_gt_f32_e32 vcc, s16, v17
	s_nop 1
	v_cndmask_b32_e32 v17, v17, v34, vcc
	v_rsq_f32_e32 v34, v17
	v_mad_i64_i32 v[16:17], s[8:9], v16, s17, v[72:73]
	v_lshl_add_u64 v[16:17], v[16:17], 0, v[48:49]
; DEVI unsigned pack2(float a, float b) { return (unsigned)f2bf(a) | ((unsigned)f2bf(b) << 16); }
; DEVI void phase_scaled(const Params& p, unsigned char* smem, const u16* A, const u16* Wt, int ntn, const float* ssq, u16* outp, int ldo) {
;     ...
; #pragma unroll
;     for (int mi = 0; mi < 4; ++mi) {
;       const int m = m0 + wm * 64 + 16 * mi + col;
;       const float rstd = rsqrtf(ssq[m] * (1.f / D) + 1e-6f);
; #pragma unroll
;       for (int ni = 0; ni < 4; ++ni) {
;         const int n = n0 + wn * 64 + 16 * ni + 4 * quad;
;         const f32x4 v = acc[ni][mi];
;         uint2 pk; pk.x = pack2(v[0] * rstd, v[1] * rstd); pk.y = pack2(v[2] * rstd, v[3] * rstd);
;         *(uint2*)(outp + (size_t)m * ldo + n) = pk;
;       }
;     }
	v_mul_f32_e32 v35, 0x45800000, v34
	v_cndmask_b32_e32 v34, v34, v35, vcc
	v_pk_mul_f32 v[30:31], v[30:31], v[34:35] op_sel_hi:[1,0]
	v_pk_mul_f32 v[32:33], v[32:33], v[34:35] op_sel_hi:[1,0]
	v_pk_mul_f32 v[26:27], v[26:27], v[34:35] op_sel_hi:[1,0]
	v_pk_mul_f32 v[22:23], v[22:23], v[34:35] op_sel_hi:[1,0]
	v_pk_mul_f32 v[20:21], v[20:21], v[34:35] op_sel_hi:[1,0]
	v_pk_mul_f32 v[18:19], v[18:19], v[34:35] op_sel_hi:[1,0]
	v_and_b32_sdwa v36, v31, v103 dst_sel:DWORD dst_unused:UNUSED_PAD src0_sel:WORD_1 src1_sel:DWORD
	v_and_b32_sdwa v37, v30, v103 dst_sel:DWORD dst_unused:UNUSED_PAD src0_sel:WORD_1 src1_sel:DWORD
	v_pk_mul_f32 v[28:29], v[28:29], v[34:35] op_sel_hi:[1,0]
	v_pk_mul_f32 v[24:25], v[24:25], v[34:35] op_sel_hi:[1,0]
	v_and_b32_sdwa v34, v33, v103 dst_sel:DWORD dst_unused:UNUSED_PAD src0_sel:WORD_1 src1_sel:DWORD
	v_and_b32_sdwa v35, v32, v103 dst_sel:DWORD dst_unused:UNUSED_PAD src0_sel:WORD_1 src1_sel:DWORD
	v_and_b32_sdwa v40, v27, v103 dst_sel:DWORD dst_unused:UNUSED_PAD src0_sel:WORD_1 src1_sel:DWORD
	v_and_b32_sdwa v41, v26, v103 dst_sel:DWORD dst_unused:UNUSED_PAD src0_sel:WORD_1 src1_sel:DWORD
	v_and_b32_sdwa v44, v23, v103 dst_sel:DWORD dst_unused:UNUSED_PAD src0_sel:WORD_1 src1_sel:DWORD
	v_and_b32_sdwa v45, v22, v103 dst_sel:DWORD dst_unused:UNUSED_PAD src0_sel:WORD_1 src1_sel:DWORD
	v_and_b32_sdwa v46, v21, v103 dst_sel:DWORD dst_unused:UNUSED_PAD src0_sel:WORD_1 src1_sel:DWORD
	v_and_b32_sdwa v47, v20, v103 dst_sel:DWORD dst_unused:UNUSED_PAD src0_sel:WORD_1 src1_sel:DWORD
	v_and_b32_sdwa v50, v19, v103 dst_sel:DWORD dst_unused:UNUSED_PAD src0_sel:WORD_1 src1_sel:DWORD
	v_and_b32_sdwa v51, v18, v103 dst_sel:DWORD dst_unused:UNUSED_PAD src0_sel:WORD_1 src1_sel:DWORD
	v_add3_u32 v31, v31, v36, s18
	v_add3_u32 v30, v30, v37, s18
	v_and_b32_sdwa v38, v29, v103 dst_sel:DWORD dst_unused:UNUSED_PAD src0_sel:WORD_1 src1_sel:DWORD
	v_and_b32_sdwa v39, v28, v103 dst_sel:DWORD dst_unused:UNUSED_PAD src0_sel:WORD_1 src1_sel:DWORD
	v_and_b32_sdwa v42, v25, v103 dst_sel:DWORD dst_unused:UNUSED_PAD src0_sel:WORD_1 src1_sel:DWORD
	v_and_b32_sdwa v43, v24, v103 dst_sel:DWORD dst_unused:UNUSED_PAD src0_sel:WORD_1 src1_sel:DWORD
	v_add3_u32 v32, v32, v35, s18
	v_add3_u32 v33, v33, v34, s18
	v_add3_u32 v27, v27, v40, s18
	v_add3_u32 v26, v26, v41, s18
	v_add3_u32 v23, v23, v44, s18
	v_add3_u32 v22, v22, v45, s18
	v_add3_u32 v34, v20, v47, s18
	v_add3_u32 v35, v21, v46, s18
	v_add3_u32 v19, v19, v50, s18
	v_add3_u32 v18, v18, v51, s18
	v_and_b32_e32 v20, 0xffff0000, v31
	v_and_b32_e32 v21, 0xffff0000, v30
	v_add3_u32 v28, v28, v39, s18
	v_add3_u32 v29, v29, v38, s18
	v_add3_u32 v24, v24, v43, s18
	v_add3_u32 v25, v25, v42, s18
	v_and_b32_e32 v27, 0xffff0000, v27
	v_and_b32_e32 v26, 0xffff0000, v26
	v_and_b32_e32 v23, 0xffff0000, v23
	v_and_b32_e32 v22, 0xffff0000, v22
	v_and_b32_e32 v30, 0xffff0000, v19
	v_and_b32_e32 v31, 0xffff0000, v18
	v_or_b32_sdwa v19, v20, v33 dst_sel:DWORD dst_unused:UNUSED_PAD src0_sel:DWORD src1_sel:WORD_1
	v_or_b32_sdwa v18, v21, v32 dst_sel:DWORD dst_unused:UNUSED_PAD src0_sel:DWORD src1_sel:WORD_1
	v_or_b32_sdwa v21, v27, v29 dst_sel:DWORD dst_unused:UNUSED_PAD src0_sel:DWORD src1_sel:WORD_1
	v_or_b32_sdwa v20, v26, v28 dst_sel:DWORD dst_unused:UNUSED_PAD src0_sel:DWORD src1_sel:WORD_1
	v_or_b32_sdwa v23, v23, v25 dst_sel:DWORD dst_unused:UNUSED_PAD src0_sel:DWORD src1_sel:WORD_1
	v_or_b32_sdwa v22, v22, v24 dst_sel:DWORD dst_unused:UNUSED_PAD src0_sel:DWORD src1_sel:WORD_1
	v_or_b32_sdwa v25, v30, v35 dst_sel:DWORD dst_unused:UNUSED_PAD src0_sel:DWORD src1_sel:WORD_1
	v_or_b32_sdwa v24, v31, v34 dst_sel:DWORD dst_unused:UNUSED_PAD src0_sel:DWORD src1_sel:WORD_1
	ds_write_b64 v180, v[18:19] offset:4096
	ds_write_b64 v181, v[20:21] offset:4096
	ds_write_b64 v182, v[22:23] offset:4096
	ds_write_b64 v183, v[24:25] offset:4096
	v_mov_b32_e32 v18, v176
	v_mov_b32_e32 v17, v14
	v_mov_b32_e32 v14, v13
	v_mov_b32_e32 v13, v10
	v_mov_b32_e32 v10, v9
	v_mov_b32_e32 v9, v6
	v_mov_b32_e32 v6, v5
	v_mov_b32_e32 v5, v2
	v_mov_b32_e32 v2, v1
	v_mov_b32_e32 v16, v12
	v_mov_b32_e32 v12, v8
	v_mov_b32_e32 v8, v4
	v_mov_b32_e32 v4, v0
	v_or_b32_e32 v0, 48, v70
	s_nop 0
	v_fmamk_f32 v1, v18, 0x3a800000, v102
	v_mul_f32_e32 v18, 0x4b800000, v1
	v_cmp_gt_f32_e32 vcc, s16, v1
	s_nop 1
	v_cndmask_b32_e32 v1, v1, v18, vcc
	v_rsq_f32_e32 v18, v1
	v_mad_i64_i32 v[0:1], s[8:9], v0, s17, v[72:73]
	v_lshl_add_u64 v[0:1], v[0:1], 0, v[48:49]
	v_mul_f32_e32 v19, 0x45800000, v18
	v_cndmask_b32_e32 v18, v18, v19, vcc
	v_pk_mul_f32 v[14:15], v[14:15], v[18:19] op_sel_hi:[1,0]
	v_pk_mul_f32 v[16:17], v[16:17], v[18:19] op_sel_hi:[1,0]
	v_pk_mul_f32 v[10:11], v[10:11], v[18:19] op_sel_hi:[1,0]
; DEVI unsigned pack2(float a, float b) { return (unsigned)f2bf(a) | ((unsigned)f2bf(b) << 16); }
; DEVI void phase_scaled(const Params& p, unsigned char* smem, const u16* A, const u16* Wt, int ntn, const float* ssq, u16* outp, int ldo) {
;     ...
; #pragma unroll
;     for (int mi = 0; mi < 4; ++mi) {
;       const int m = m0 + wm * 64 + 16 * mi + col;
;       const float rstd = rsqrtf(ssq[m] * (1.f / D) + 1e-6f);
; #pragma unroll
;       for (int ni = 0; ni < 4; ++ni) {
;         const int n = n0 + wn * 64 + 16 * ni + 4 * quad;
;         const f32x4 v = acc[ni][mi];
;         uint2 pk; pk.x = pack2(v[0] * rstd, v[1] * rstd); pk.y = pack2(v[2] * rstd, v[3] * rstd);
;         *(uint2*)(outp + (size_t)m * ldo + n) = pk;
;       }
;     }
	v_pk_mul_f32 v[6:7], v[6:7], v[18:19] op_sel_hi:[1,0]
	v_pk_mul_f32 v[4:5], v[4:5], v[18:19] op_sel_hi:[1,0]
	v_pk_mul_f32 v[2:3], v[2:3], v[18:19] op_sel_hi:[1,0]
	v_and_b32_sdwa v20, v15, v103 dst_sel:DWORD dst_unused:UNUSED_PAD src0_sel:WORD_1 src1_sel:DWORD
	v_and_b32_sdwa v21, v14, v103 dst_sel:DWORD dst_unused:UNUSED_PAD src0_sel:WORD_1 src1_sel:DWORD
	v_pk_mul_f32 v[12:13], v[12:13], v[18:19] op_sel_hi:[1,0]
	v_pk_mul_f32 v[8:9], v[8:9], v[18:19] op_sel_hi:[1,0]
	v_and_b32_sdwa v18, v17, v103 dst_sel:DWORD dst_unused:UNUSED_PAD src0_sel:WORD_1 src1_sel:DWORD
	v_and_b32_sdwa v19, v16, v103 dst_sel:DWORD dst_unused:UNUSED_PAD src0_sel:WORD_1 src1_sel:DWORD
	v_and_b32_sdwa v24, v11, v103 dst_sel:DWORD dst_unused:UNUSED_PAD src0_sel:WORD_1 src1_sel:DWORD
	v_and_b32_sdwa v25, v10, v103 dst_sel:DWORD dst_unused:UNUSED_PAD src0_sel:WORD_1 src1_sel:DWORD
	v_and_b32_sdwa v28, v7, v103 dst_sel:DWORD dst_unused:UNUSED_PAD src0_sel:WORD_1 src1_sel:DWORD
	v_and_b32_sdwa v29, v6, v103 dst_sel:DWORD dst_unused:UNUSED_PAD src0_sel:WORD_1 src1_sel:DWORD
	v_and_b32_sdwa v30, v5, v103 dst_sel:DWORD dst_unused:UNUSED_PAD src0_sel:WORD_1 src1_sel:DWORD
	v_and_b32_sdwa v31, v4, v103 dst_sel:DWORD dst_unused:UNUSED_PAD src0_sel:WORD_1 src1_sel:DWORD
	v_and_b32_sdwa v32, v3, v103 dst_sel:DWORD dst_unused:UNUSED_PAD src0_sel:WORD_1 src1_sel:DWORD
	v_and_b32_sdwa v33, v2, v103 dst_sel:DWORD dst_unused:UNUSED_PAD src0_sel:WORD_1 src1_sel:DWORD
	v_add3_u32 v15, v15, v20, s18
	v_add3_u32 v14, v14, v21, s18
	v_and_b32_sdwa v22, v13, v103 dst_sel:DWORD dst_unused:UNUSED_PAD src0_sel:WORD_1 src1_sel:DWORD
	v_and_b32_sdwa v23, v12, v103 dst_sel:DWORD dst_unused:UNUSED_PAD src0_sel:WORD_1 src1_sel:DWORD
	v_and_b32_sdwa v26, v9, v103 dst_sel:DWORD dst_unused:UNUSED_PAD src0_sel:WORD_1 src1_sel:DWORD
	v_and_b32_sdwa v27, v8, v103 dst_sel:DWORD dst_unused:UNUSED_PAD src0_sel:WORD_1 src1_sel:DWORD
	v_add3_u32 v16, v16, v19, s18
	v_add3_u32 v17, v17, v18, s18
	v_add3_u32 v11, v11, v24, s18
	v_add3_u32 v10, v10, v25, s18
	v_add3_u32 v7, v7, v28, s18
	v_add3_u32 v6, v6, v29, s18
	v_add3_u32 v18, v4, v31, s18
	v_add3_u32 v19, v5, v30, s18
	v_add3_u32 v3, v3, v32, s18
	v_add3_u32 v2, v2, v33, s18
	v_and_b32_e32 v4, 0xffff0000, v15
	v_and_b32_e32 v5, 0xffff0000, v14
	v_add3_u32 v12, v12, v23, s18
	v_add3_u32 v13, v13, v22, s18
	v_add3_u32 v8, v8, v27, s18
	v_add3_u32 v9, v9, v26, s18
	v_and_b32_e32 v11, 0xffff0000, v11
	v_and_b32_e32 v10, 0xffff0000, v10
	v_and_b32_e32 v7, 0xffff0000, v7
	v_and_b32_e32 v6, 0xffff0000, v6
	v_and_b32_e32 v14, 0xffff0000, v3
	v_and_b32_e32 v15, 0xffff0000, v2
	v_or_b32_sdwa v3, v4, v17 dst_sel:DWORD dst_unused:UNUSED_PAD src0_sel:DWORD src1_sel:WORD_1
	v_or_b32_sdwa v2, v5, v16 dst_sel:DWORD dst_unused:UNUSED_PAD src0_sel:DWORD src1_sel:WORD_1
	v_or_b32_sdwa v5, v11, v13 dst_sel:DWORD dst_unused:UNUSED_PAD src0_sel:DWORD src1_sel:WORD_1
	v_or_b32_sdwa v4, v10, v12 dst_sel:DWORD dst_unused:UNUSED_PAD src0_sel:DWORD src1_sel:WORD_1
	v_or_b32_sdwa v7, v7, v9 dst_sel:DWORD dst_unused:UNUSED_PAD src0_sel:DWORD src1_sel:WORD_1
	v_or_b32_sdwa v6, v6, v8 dst_sel:DWORD dst_unused:UNUSED_PAD src0_sel:DWORD src1_sel:WORD_1
	v_or_b32_sdwa v9, v14, v19 dst_sel:DWORD dst_unused:UNUSED_PAD src0_sel:DWORD src1_sel:WORD_1
	v_or_b32_sdwa v8, v15, v18 dst_sel:DWORD dst_unused:UNUSED_PAD src0_sel:DWORD src1_sel:WORD_1
	ds_write_b64 v180, v[2:3] offset:6144
	ds_write_b64 v181, v[4:5] offset:6144
	ds_write_b64 v182, v[6:7] offset:6144
	ds_write_b64 v183, v[8:9] offset:6144
	s_waitcnt lgkmcnt(0)
	ds_read_b128 v[212:215], v184 offset:0
	ds_read_b128 v[216:219], v184 offset:1024
	ds_read_b128 v[220:223], v184 offset:2048
	ds_read_b128 v[224:227], v184 offset:3072
	ds_read_b128 v[228:231], v184 offset:4096
	ds_read_b128 v[232:235], v184 offset:5120
	ds_read_b128 v[236:239], v184 offset:6144
	ds_read_b128 v[240:243], v184 offset:7168
	s_waitcnt lgkmcnt(7)
	global_store_dwordx4 v185, v[212:215], s[98:99]
	v_add_u32_e32 v185, v185, v186
	s_waitcnt lgkmcnt(6)
	global_store_dwordx4 v185, v[216:219], s[98:99]
	v_add_u32_e32 v185, v185, v186
	s_waitcnt lgkmcnt(5)
	global_store_dwordx4 v185, v[220:223], s[98:99]
	v_add_u32_e32 v185, v185, v186
	s_waitcnt lgkmcnt(4)
	global_store_dwordx4 v185, v[224:227], s[98:99]
	v_add_u32_e32 v185, v185, v186
	s_waitcnt lgkmcnt(3)
	global_store_dwordx4 v185, v[228:231], s[98:99]
	v_add_u32_e32 v185, v185, v186
	s_waitcnt lgkmcnt(2)
	global_store_dwordx4 v185, v[232:235], s[98:99]
	v_add_u32_e32 v185, v185, v186
	s_waitcnt lgkmcnt(1)
	global_store_dwordx4 v185, v[236:239], s[98:99]
	v_add_u32_e32 v185, v185, v186
	s_waitcnt lgkmcnt(0)
	global_store_dwordx4 v185, v[240:243], s[98:99]
	s_barrier
	s_cbranch_scc0 .LBB0_1163

; #define LAS __attribute__((address_space(3)))
; template <bool COOP>
; __global__ void __launch_bounds__(256, 2) mega(Params p, int ph_lo, int ph_hi) {
;   __shared__ __attribute__((aligned(16))) unsigned char smem[SMEM_BYTES];
;   __shared__ uint4 xb_words;
;   if (threadIdx.x == 0) xb_words = make_uint4(0u, 0u, 0u, 0u);
;   __syncthreads();
;   XcdBarrier xb = xcd_barrier_post(p.bar, (volatile LAS unsigned*)&xb_words);
;   (void)xb;
;   if (COOP && ph_hi > 1000) cg::this_grid().sync();
	.amdhsa_kernel _Z4megaILb1EEv6Paramsii
		.amdhsa_group_segment_fixed_size 73744
		.amdhsa_private_segment_fixed_size 0
		.amdhsa_kernarg_size 768
		.amdhsa_user_sgpr_count 2
		.amdhsa_user_sgpr_dispatch_ptr 0
		.amdhsa_user_sgpr_queue_ptr 0
		.amdhsa_user_sgpr_kernarg_segment_ptr 1
		.amdhsa_user_sgpr_dispatch_id 0
		.amdhsa_user_sgpr_kernarg_preload_length 0
		.amdhsa_user_sgpr_kernarg_preload_offset 0
		.amdhsa_user_sgpr_private_segment_size 0
		.amdhsa_uses_dynamic_stack 0
		.amdhsa_enable_private_segment 0
		.amdhsa_system_sgpr_workgroup_id_x 1
		.amdhsa_system_sgpr_workgroup_id_y 0
		.amdhsa_system_sgpr_workgroup_id_z 0
		.amdhsa_system_sgpr_workgroup_info 0
		.amdhsa_system_vgpr_workitem_id 2
		.amdhsa_next_free_vgpr 249
		.amdhsa_next_free_sgpr 100
		.amdhsa_accum_offset 252
		.amdhsa_reserve_vcc 1
		.amdhsa_float_round_mode_32 0
		.amdhsa_float_round_mode_16_64 0
		.amdhsa_float_denorm_mode_32 3
		.amdhsa_float_denorm_mode_16_64 3
		.amdhsa_dx10_clamp 1
		.amdhsa_ieee_mode 1
		.amdhsa_fp16_overflow 0
		.amdhsa_tg_split 0
		.amdhsa_exception_fp_ieee_invalid_op 0
		.amdhsa_exception_fp_denorm_src 0
		.amdhsa_exception_fp_ieee_div_zero 0
		.amdhsa_exception_fp_ieee_overflow 0
		.amdhsa_exception_fp_ieee_underflow 0
		.amdhsa_exception_fp_ieee_inexact 0
		.amdhsa_exception_int_div_zero 0
	.end_amdhsa_kernel

; #define LAS __attribute__((address_space(3)))
; template <bool COOP>
; __global__ void __launch_bounds__(256, 2) mega(Params p, int ph_lo, int ph_hi) {
;   __shared__ __attribute__((aligned(16))) unsigned char smem[SMEM_BYTES];
;   __shared__ uint4 xb_words;
;   if (threadIdx.x == 0) xb_words = make_uint4(0u, 0u, 0u, 0u);
;   __syncthreads();
;   XcdBarrier xb = xcd_barrier_post(p.bar, (volatile LAS unsigned*)&xb_words);
;   (void)xb;
;   if (COOP && ph_hi > 1000) cg::this_grid().sync();
amdhsa.kernels:
  - .agpr_count:     0
    .args:
      - .offset:         0
        .size:           504
        .value_kind:     by_value
      - .offset:         504
        .size:           4
        .value_kind:     by_value
      - .offset:         508
        .size:           4
        .value_kind:     by_value
      - .offset:         512
        .size:           4
        .value_kind:     hidden_block_count_x
      - .offset:         516
        .size:           4
        .value_kind:     hidden_block_count_y
      - .offset:         520
        .size:           4
        .value_kind:     hidden_block_count_z
      - .offset:         524
        .size:           2
        .value_kind:     hidden_group_size_x
      - .offset:         526
        .size:           2
        .value_kind:     hidden_group_size_y
      - .offset:         528
        .size:           2
        .value_kind:     hidden_group_size_z
      - .offset:         530
        .size:           2
        .value_kind:     hidden_remainder_x
      - .offset:         532
        .size:           2
        .value_kind:     hidden_remainder_y
      - .offset:         534
        .size:           2
        .value_kind:     hidden_remainder_z
      - .offset:         552
        .size:           8
        .value_kind:     hidden_global_offset_x
      - .offset:         560
        .size:           8
        .value_kind:     hidden_global_offset_y
      - .offset:         568
        .size:           8
        .value_kind:     hidden_global_offset_z
      - .offset:         576
        .size:           2
        .value_kind:     hidden_grid_dims
      - .offset:         600
        .size:           8
        .value_kind:     hidden_multigrid_sync_arg
    .group_segment_fixed_size: 73744
    .kernarg_segment_align: 8
    .kernarg_segment_size: 768
    .language:       OpenCL C
    .language_version:
      - 2
      - 0
    .max_flat_workgroup_size: 256
    .name:           _Z4megaILb1EEv6Paramsii
    .private_segment_fixed_size: 0
    .sgpr_count:     106
    .sgpr_spill_count: 122
    .symbol:         _Z4megaILb1EEv6Paramsii.kd
    .uniform_work_group_size: 1
    .uses_dynamic_stack: false
    .vgpr_count:     249
    .vgpr_spill_count: 0
    .wavefront_size: 64
